# odd-layer post-pass: all of a row's loads (raw segments, gains, rope tables) issued together at the row top into their own registers with one wait, instead of a load-wait per head group
# speedup vs baseline: 1.0050x; 1.0050x over previous
.LBB0_458:
	s_add_i32 s8, s19, s23
	s_cmpk_lt_i32 s8, 0x1000
	s_cselect_b64 s[16:17], -1, 0
	s_and_b32 s9, s8, 0x3ff
	s_and_b32 s21, s8, 0xff
	s_cmpk_gt_i32 s8, 0xfff
	s_cselect_b64 s[58:59], -1, 0
	s_and_b64 s[60:61], s[58:59], exec
	s_cselect_b32 s12, s9, s21
	s_ashr_i32 s9, s8, 31
	s_mul_i32 s10, s8, 0x1600
	s_mul_hi_i32 s11, s8, 0x1600
	s_add_u32 s10, s15, s10
	s_addc_u32 s11, s18, s11
	s_waitcnt lgkmcnt(0)
	global_load_dwordx2 v[20:21], v56, s[10:11]
	global_load_dwordx4 v[16:19], v[28:29], off
	s_and_b32 s13, s12, 63
	s_lshr_b32 s12, s12, 6
	v_mov_b32_e32 v2, s12
	v_mov_b32_e32 v5, s13
	v_cndmask_b32_e64 v2, v2, v5, s[50:51]
	v_lshlrev_b32_e32 v2, 6, v2
	v_lshl_add_u64 v[8:9], v[26:27], 0, v[2:3]
	global_load_dwordx4 v[12:15], v[8:9], off
	v_lshl_add_u64 v[8:9], v[24:25], 0, v[2:3]
	global_load_dwordx4 v[8:11], v[8:9], off
	s_lshl_b32 s20, s21, 8
	global_load_dwordx4 v[104:107], v[28:29], off
	v_add_u32_e32 v148, 0x1000, v4
	v_add_u32_e32 v149, 0x1000, v58
	global_load_dwordx2 v[100:101], v74, s[10:11] offset:512
	global_load_dwordx2 v[102:103], v74, s[10:11] offset:1024
	global_load_dwordx2 v[108:109], v74, s[10:11] offset:1536
	global_load_dwordx2 v[110:111], v56, s[10:11] offset:2048
	global_load_dwordx4 v[112:115], v[30:31], off
	global_load_dwordx2 v[116:117], v56, s[10:11] offset:2560
	global_load_dwordx4 v[120:123], v4, s[10:11] offset:3072
	global_load_dwordx4 v[124:127], v[36:37], off offset:16
	global_load_dwordx4 v[128:131], v[36:37], off
	global_load_dwordx4 v[132:135], v148, s[10:11]
	global_load_dwordx4 v[136:139], v[40:41], off offset:16
	global_load_dwordx4 v[140:143], v[40:41], off
	global_load_dwordx2 v[144:145], v149, s[10:11] offset:1024
	s_waitcnt vmcnt(0)
	v_lshlrev_b32_e32 v23, 16, v21
	v_lshlrev_b32_e32 v22, 16, v20
	v_and_b32_e32 v21, 0xffff0000, v21
	v_and_b32_e32 v20, 0xffff0000, v20
	v_pk_mul_f32 v[76:77], v[20:21], v[20:21]
	s_nop 0
	v_pk_fma_f32 v[76:77], v[22:23], v[22:23], v[76:77]
	s_nop 0
	v_add_f32_e32 v2, v76, v77
	v_mov_b32_e32 v77, v20
	v_mov_b32_e32 v76, v22
	s_nop 1
	v_add_f32_dpp v2, v2, v2 quad_perm:[1,0,3,2] row_mask:0xf bank_mask:0xf
	s_nop 1
	v_add_f32_dpp v2, v2, v2 quad_perm:[2,3,0,1] row_mask:0xf bank_mask:0xf
	s_nop 1
	v_add_f32_dpp v2, v2, v2 row_half_mirror row_mask:0xf bank_mask:0xf
	s_nop 1
	v_add_f32_dpp v2, v2, v2 row_mirror row_mask:0xf bank_mask:0xf
	v_fmamk_f32 v2, v2, 0x3c800000, v234
	v_mul_f32_e32 v5, 0x4f800000, v2
	v_cmp_gt_f32_e32 vcc, s3, v2
	s_nop 1
	v_cndmask_b32_e32 v2, v2, v5, vcc
	v_sqrt_f32_e32 v5, v2
	s_nop 0
	v_add_u32_e32 v20, -1, v5
	v_add_u32_e32 v22, 1, v5
	v_fma_f32 v57, -v20, v5, v2
	v_fma_f32 v59, -v22, v5, v2
	v_cmp_ge_f32_e64 s[62:63], 0, v57
	s_nop 1
	v_cndmask_b32_e64 v5, v5, v20, s[62:63]
	v_cmp_lt_f32_e64 s[62:63], 0, v59
	s_nop 1
	v_cndmask_b32_e64 v5, v5, v22, s[62:63]
	v_mul_f32_e32 v20, 0x37800000, v5
	v_cndmask_b32_e32 v5, v5, v20, vcc
	v_cmp_class_f32_e32 vcc, v2, v235
	v_mov_b32_e32 v20, v23
	s_nop 0
	v_cndmask_b32_e32 v2, v5, v2, vcc
	v_div_scale_f32 v5, s[12:13], v2, v2, 1.0
	v_rcp_f32_e32 v22, v5
	v_div_scale_f32 v23, vcc, 1.0, v2, 1.0
	s_lshl_b64 s[12:13], s[8:9], 11
	v_fma_f32 v57, -v5, v22, 1.0
	v_fmac_f32_e32 v22, v57, v22
	v_mul_f32_e32 v57, v23, v22
	v_fma_f32 v59, -v5, v57, v23
	v_fmac_f32_e32 v57, v59, v22
	v_fma_f32 v5, -v5, v57, v23
	v_div_fmas_f32 v5, v5, v22, v57
	v_div_fixup_f32 v2, v5, v2, 1.0
	v_pk_mul_f32 v[22:23], v[2:3], v[76:77] op_sel_hi:[0,1]
	v_pk_mul_f32 v[20:21], v[2:3], v[20:21] op_sel_hi:[0,1]
	v_pk_mul_f32 v[18:19], v[18:19], v[20:21]
	v_pk_mul_f32 v[20:21], v[16:17], v[22:23]
	ds_bpermute_b32 v22, v70, v20
	ds_bpermute_b32 v23, v70, v21
	ds_bpermute_b32 v76, v70, v18
	ds_bpermute_b32 v77, v70, v19
	v_lshl_add_u64 v[16:17], v[54:55], 0, s[12:13]
	s_waitcnt lgkmcnt(2)
	v_pk_mul_f32 v[22:23], v[12:13], v[22:23]
	s_nop 0
	v_xor_b32_e32 v57, 0x80000000, v22
	s_waitcnt lgkmcnt(0)
	v_pk_mul_f32 v[76:77], v[14:15], v[76:77]
	v_xor_b32_e32 v59, 0x80000000, v23
	v_xor_b32_e32 v2, 0x80000000, v76
	v_xor_b32_e32 v5, 0x80000000, v77
	v_cndmask_b32_e64 v23, v23, v59, s[52:53]
	v_cndmask_b32_e64 v22, v22, v57, s[52:53]
	v_cndmask_b32_e64 v77, v77, v5, s[52:53]
	v_cndmask_b32_e64 v76, v76, v2, s[52:53]
	v_pk_fma_f32 v[76:77], v[10:11], v[18:19], v[76:77]
	v_pk_fma_f32 v[22:23], v[8:9], v[20:21], v[22:23]
	v_cndmask_b32_e64 v19, v19, v77, s[58:59]
	v_cndmask_b32_e64 v21, v21, v23, s[58:59]
	v_cndmask_b32_e64 v20, v20, v22, s[58:59]
	v_cndmask_b32_e64 v18, v18, v76, s[58:59]
	v_pk_mul_f32 v[18:19], v[18:19], s[46:47] op_sel_hi:[1,0]
	v_pk_mul_f32 v[20:21], v[20:21], s[46:47] op_sel_hi:[1,0]
	s_nop 0
	v_cvt_pk_bf16_f32 v20, v20, v21
	v_cvt_pk_bf16_f32 v21, v18, v19
	global_store_dwordx2 v[16:17], v[20:21], off
	s_nop 0
	v_lshlrev_b32_e32 v77, 16, v101
	v_lshlrev_b32_e32 v76, 16, v100
	v_and_b32_e32 v23, 0xffff0000, v101
	v_and_b32_e32 v22, 0xffff0000, v100
	v_pk_mul_f32 v[78:79], v[22:23], v[22:23]
	s_nop 0
	v_pk_fma_f32 v[78:79], v[76:77], v[76:77], v[78:79]
	s_nop 0
	v_add_f32_e32 v2, v78, v79
	v_mov_b32_e32 v79, v22
	v_mov_b32_e32 v78, v76
	s_nop 1
	v_add_f32_dpp v2, v2, v2 quad_perm:[1,0,3,2] row_mask:0xf bank_mask:0xf
	s_nop 1
	v_add_f32_dpp v2, v2, v2 quad_perm:[2,3,0,1] row_mask:0xf bank_mask:0xf
	s_nop 1
	v_add_f32_dpp v2, v2, v2 row_half_mirror row_mask:0xf bank_mask:0xf
	s_nop 1
	v_add_f32_dpp v2, v2, v2 row_mirror row_mask:0xf bank_mask:0xf
	v_fmamk_f32 v2, v2, 0x3c800000, v234
	v_mul_f32_e32 v5, 0x4f800000, v2
	v_cmp_gt_f32_e32 vcc, s3, v2
	s_nop 1
	v_cndmask_b32_e32 v2, v2, v5, vcc
	v_sqrt_f32_e32 v5, v2
	s_nop 0
	v_add_u32_e32 v22, -1, v5
	v_add_u32_e32 v57, 1, v5
	v_fma_f32 v59, -v22, v5, v2
	v_fma_f32 v75, -v57, v5, v2
	v_cmp_ge_f32_e64 s[62:63], 0, v59
	s_nop 1
	v_cndmask_b32_e64 v5, v5, v22, s[62:63]
	v_cmp_lt_f32_e64 s[62:63], 0, v75
	s_nop 1
	v_cndmask_b32_e64 v5, v5, v57, s[62:63]
	v_mul_f32_e32 v22, 0x37800000, v5
	v_cndmask_b32_e32 v5, v5, v22, vcc
	v_cmp_class_f32_e32 vcc, v2, v235
	v_mov_b32_e32 v22, v77
	s_nop 0
	v_cndmask_b32_e32 v2, v5, v2, vcc
	v_div_scale_f32 v5, s[12:13], v2, v2, 1.0
	v_rcp_f32_e32 v57, v5
	v_div_scale_f32 v59, vcc, 1.0, v2, 1.0
	v_fma_f32 v75, -v5, v57, 1.0
	v_fmac_f32_e32 v57, v75, v57
	v_mul_f32_e32 v75, v59, v57
	v_fma_f32 v76, -v5, v75, v59
	v_fmac_f32_e32 v75, v76, v57
	v_fma_f32 v5, -v5, v75, v59
	v_div_fmas_f32 v5, v5, v57, v75
	v_div_fixup_f32 v2, v5, v2, 1.0
	v_pk_mul_f32 v[76:77], v[2:3], v[78:79] op_sel_hi:[0,1]
	v_pk_mul_f32 v[22:23], v[2:3], v[22:23] op_sel_hi:[0,1]
	v_pk_mul_f32 v[20:21], v[106:107], v[22:23]
	v_pk_mul_f32 v[18:19], v[104:105], v[76:77]
	ds_bpermute_b32 v22, v70, v18
	ds_bpermute_b32 v23, v70, v19
	ds_bpermute_b32 v76, v70, v20
	ds_bpermute_b32 v77, v70, v21
	s_waitcnt lgkmcnt(2)
	v_pk_mul_f32 v[22:23], v[12:13], v[22:23]
	s_nop 0
	v_xor_b32_e32 v57, 0x80000000, v22
	s_waitcnt lgkmcnt(0)
	v_pk_mul_f32 v[76:77], v[14:15], v[76:77]
	v_xor_b32_e32 v59, 0x80000000, v23
	v_xor_b32_e32 v2, 0x80000000, v76
	v_xor_b32_e32 v5, 0x80000000, v77
	v_cndmask_b32_e64 v23, v23, v59, s[52:53]
	v_cndmask_b32_e64 v22, v22, v57, s[52:53]
	v_cndmask_b32_e64 v77, v77, v5, s[52:53]
	v_cndmask_b32_e64 v76, v76, v2, s[52:53]
	v_pk_fma_f32 v[76:77], v[10:11], v[20:21], v[76:77]
	v_pk_fma_f32 v[22:23], v[8:9], v[18:19], v[22:23]
	v_cndmask_b32_e64 v21, v21, v77, s[58:59]
	v_cndmask_b32_e64 v19, v19, v23, s[58:59]
	v_cndmask_b32_e64 v18, v18, v22, s[58:59]
	v_cndmask_b32_e64 v20, v20, v76, s[58:59]
	v_pk_mul_f32 v[20:21], v[20:21], s[46:47] op_sel_hi:[1,0]
	v_pk_mul_f32 v[18:19], v[18:19], s[46:47] op_sel_hi:[1,0]
	s_nop 0
	v_cvt_pk_bf16_f32 v18, v18, v19
	v_cvt_pk_bf16_f32 v19, v20, v21
	global_store_dwordx2 v[16:17], v[18:19], off offset:512
	s_nop 0
	v_lshlrev_b32_e32 v77, 16, v103
	v_lshlrev_b32_e32 v76, 16, v102
	v_and_b32_e32 v23, 0xffff0000, v103
	v_and_b32_e32 v22, 0xffff0000, v102
	v_pk_mul_f32 v[78:79], v[22:23], v[22:23]
	s_nop 0
	v_pk_fma_f32 v[78:79], v[76:77], v[76:77], v[78:79]
	s_nop 0
	v_add_f32_e32 v2, v78, v79
	v_mov_b32_e32 v79, v22
	v_mov_b32_e32 v78, v76
	s_nop 1
	v_add_f32_dpp v2, v2, v2 quad_perm:[1,0,3,2] row_mask:0xf bank_mask:0xf
	s_nop 1
	v_add_f32_dpp v2, v2, v2 quad_perm:[2,3,0,1] row_mask:0xf bank_mask:0xf
	s_nop 1
	v_add_f32_dpp v2, v2, v2 row_half_mirror row_mask:0xf bank_mask:0xf
	s_nop 1
	v_add_f32_dpp v2, v2, v2 row_mirror row_mask:0xf bank_mask:0xf
	v_fmamk_f32 v2, v2, 0x3c800000, v234
	v_mul_f32_e32 v5, 0x4f800000, v2
	v_cmp_gt_f32_e32 vcc, s3, v2
	s_nop 1
	v_cndmask_b32_e32 v2, v2, v5, vcc
	v_sqrt_f32_e32 v5, v2
	s_nop 0
	v_add_u32_e32 v22, -1, v5
	v_add_u32_e32 v57, 1, v5
	v_fma_f32 v59, -v22, v5, v2
	v_fma_f32 v75, -v57, v5, v2
	v_cmp_ge_f32_e64 s[62:63], 0, v59
	s_nop 1
	v_cndmask_b32_e64 v5, v5, v22, s[62:63]
	v_cmp_lt_f32_e64 s[62:63], 0, v75
	s_nop 1
	v_cndmask_b32_e64 v5, v5, v57, s[62:63]
	v_mul_f32_e32 v22, 0x37800000, v5
	v_cndmask_b32_e32 v5, v5, v22, vcc
	v_cmp_class_f32_e32 vcc, v2, v235
	v_mov_b32_e32 v22, v77
	s_nop 0
	v_cndmask_b32_e32 v2, v5, v2, vcc
	v_div_scale_f32 v5, s[12:13], v2, v2, 1.0
	v_rcp_f32_e32 v57, v5
	v_div_scale_f32 v59, vcc, 1.0, v2, 1.0
	v_fma_f32 v75, -v5, v57, 1.0
	v_fmac_f32_e32 v57, v75, v57
	v_mul_f32_e32 v75, v59, v57
	v_fma_f32 v76, -v5, v75, v59
	v_fmac_f32_e32 v75, v76, v57
	v_fma_f32 v5, -v5, v75, v59
	v_div_fmas_f32 v5, v5, v57, v75
	v_div_fixup_f32 v2, v5, v2, 1.0
	v_pk_mul_f32 v[76:77], v[2:3], v[78:79] op_sel_hi:[0,1]
	v_pk_mul_f32 v[22:23], v[2:3], v[22:23] op_sel_hi:[0,1]
	v_pk_mul_f32 v[20:21], v[106:107], v[22:23]
	v_pk_mul_f32 v[18:19], v[104:105], v[76:77]
	ds_bpermute_b32 v22, v70, v18
	ds_bpermute_b32 v23, v70, v19
	ds_bpermute_b32 v76, v70, v20
	ds_bpermute_b32 v77, v70, v21
	s_waitcnt lgkmcnt(2)
	v_pk_mul_f32 v[22:23], v[12:13], v[22:23]
	s_nop 0
	v_xor_b32_e32 v57, 0x80000000, v22
	s_waitcnt lgkmcnt(0)
	v_pk_mul_f32 v[76:77], v[14:15], v[76:77]
	v_xor_b32_e32 v59, 0x80000000, v23
	v_xor_b32_e32 v2, 0x80000000, v76
	v_xor_b32_e32 v5, 0x80000000, v77
	v_cndmask_b32_e64 v23, v23, v59, s[52:53]
	v_cndmask_b32_e64 v22, v22, v57, s[52:53]
	v_cndmask_b32_e64 v77, v77, v5, s[52:53]
	v_cndmask_b32_e64 v76, v76, v2, s[52:53]
	v_pk_fma_f32 v[76:77], v[10:11], v[20:21], v[76:77]
	v_pk_fma_f32 v[22:23], v[8:9], v[18:19], v[22:23]
	v_cndmask_b32_e64 v21, v21, v77, s[58:59]
	v_cndmask_b32_e64 v19, v19, v23, s[58:59]
	v_cndmask_b32_e64 v18, v18, v22, s[58:59]
	v_cndmask_b32_e64 v20, v20, v76, s[58:59]
	v_pk_mul_f32 v[20:21], v[20:21], s[46:47] op_sel_hi:[1,0]
	v_pk_mul_f32 v[18:19], v[18:19], s[46:47] op_sel_hi:[1,0]
	s_nop 0
	v_cvt_pk_bf16_f32 v18, v18, v19
	v_cvt_pk_bf16_f32 v19, v20, v21
	global_store_dwordx2 v[16:17], v[18:19], off offset:1024
	s_nop 0
	v_lshlrev_b32_e32 v77, 16, v109
	v_lshlrev_b32_e32 v76, 16, v108
	v_and_b32_e32 v23, 0xffff0000, v109
	v_and_b32_e32 v22, 0xffff0000, v108
	v_pk_mul_f32 v[78:79], v[22:23], v[22:23]
	s_nop 0
	v_pk_fma_f32 v[78:79], v[76:77], v[76:77], v[78:79]
	s_nop 0
	v_add_f32_e32 v2, v78, v79
	v_mov_b32_e32 v79, v22
	v_mov_b32_e32 v78, v76
	s_nop 1
	v_add_f32_dpp v2, v2, v2 quad_perm:[1,0,3,2] row_mask:0xf bank_mask:0xf
	s_nop 1
	v_add_f32_dpp v2, v2, v2 quad_perm:[2,3,0,1] row_mask:0xf bank_mask:0xf
	s_nop 1
	v_add_f32_dpp v2, v2, v2 row_half_mirror row_mask:0xf bank_mask:0xf
	s_nop 1
	v_add_f32_dpp v2, v2, v2 row_mirror row_mask:0xf bank_mask:0xf
	v_fmamk_f32 v2, v2, 0x3c800000, v234
	v_mul_f32_e32 v5, 0x4f800000, v2
	v_cmp_gt_f32_e32 vcc, s3, v2
	s_nop 1
	v_cndmask_b32_e32 v2, v2, v5, vcc
	v_sqrt_f32_e32 v5, v2
	s_nop 0
	v_add_u32_e32 v22, -1, v5
	v_add_u32_e32 v57, 1, v5
	v_fma_f32 v59, -v22, v5, v2
	v_fma_f32 v75, -v57, v5, v2
	v_cmp_ge_f32_e64 s[62:63], 0, v59
	s_nop 1
	v_cndmask_b32_e64 v5, v5, v22, s[62:63]
	v_cmp_lt_f32_e64 s[62:63], 0, v75
	s_nop 1
	v_cndmask_b32_e64 v5, v5, v57, s[62:63]
	v_mul_f32_e32 v22, 0x37800000, v5
	v_cndmask_b32_e32 v5, v5, v22, vcc
	v_cmp_class_f32_e32 vcc, v2, v235
	v_mov_b32_e32 v22, v77
	s_nop 0
	v_cndmask_b32_e32 v2, v5, v2, vcc
	v_div_scale_f32 v5, s[12:13], v2, v2, 1.0
	v_rcp_f32_e32 v57, v5
	v_div_scale_f32 v59, vcc, 1.0, v2, 1.0
	v_fma_f32 v75, -v5, v57, 1.0
	v_fmac_f32_e32 v57, v75, v57
	v_mul_f32_e32 v75, v59, v57
	v_fma_f32 v76, -v5, v75, v59
	v_fmac_f32_e32 v75, v76, v57
	v_fma_f32 v5, -v5, v75, v59
	v_div_fmas_f32 v5, v5, v57, v75
	v_div_fixup_f32 v2, v5, v2, 1.0
	v_pk_mul_f32 v[76:77], v[2:3], v[78:79] op_sel_hi:[0,1]
	v_pk_mul_f32 v[22:23], v[2:3], v[22:23] op_sel_hi:[0,1]
	v_pk_mul_f32 v[20:21], v[106:107], v[22:23]
	v_pk_mul_f32 v[18:19], v[104:105], v[76:77]
	ds_bpermute_b32 v22, v70, v18
	ds_bpermute_b32 v23, v70, v19
	ds_bpermute_b32 v76, v70, v20
	ds_bpermute_b32 v77, v70, v21
	s_waitcnt lgkmcnt(2)
	v_pk_mul_f32 v[22:23], v[12:13], v[22:23]
	s_nop 0
	v_xor_b32_e32 v57, 0x80000000, v22
	s_waitcnt lgkmcnt(0)
	v_pk_mul_f32 v[76:77], v[14:15], v[76:77]
	v_xor_b32_e32 v59, 0x80000000, v23
	v_xor_b32_e32 v2, 0x80000000, v76
	v_xor_b32_e32 v5, 0x80000000, v77
	v_cndmask_b32_e64 v23, v23, v59, s[52:53]
	v_cndmask_b32_e64 v22, v22, v57, s[52:53]
	v_cndmask_b32_e64 v77, v77, v5, s[52:53]
	v_cndmask_b32_e64 v76, v76, v2, s[52:53]
	v_pk_fma_f32 v[76:77], v[10:11], v[20:21], v[76:77]
	v_pk_fma_f32 v[22:23], v[8:9], v[18:19], v[22:23]
	v_cndmask_b32_e64 v21, v21, v77, s[58:59]
	v_cndmask_b32_e64 v19, v19, v23, s[58:59]
	v_cndmask_b32_e64 v18, v18, v22, s[58:59]
	v_cndmask_b32_e64 v20, v20, v76, s[58:59]
	v_pk_mul_f32 v[20:21], v[20:21], s[46:47] op_sel_hi:[1,0]
	v_pk_mul_f32 v[18:19], v[18:19], s[46:47] op_sel_hi:[1,0]
	s_nop 0
	v_cvt_pk_bf16_f32 v18, v18, v19
	v_cvt_pk_bf16_f32 v19, v20, v21
	global_store_dwordx2 v[16:17], v[18:19], off offset:1536
	s_nop 0
	v_lshlrev_b32_e32 v23, 16, v111
	v_lshlrev_b32_e32 v22, 16, v110
	v_and_b32_e32 v21, 0xffff0000, v111
	v_and_b32_e32 v20, 0xffff0000, v110
	v_pk_mul_f32 v[76:77], v[20:21], v[20:21]
	s_nop 0
	v_pk_fma_f32 v[76:77], v[22:23], v[22:23], v[76:77]
	s_nop 0
	v_add_f32_e32 v2, v76, v77
	v_mov_b32_e32 v77, v20
	v_mov_b32_e32 v76, v22
	s_nop 1
	v_add_f32_dpp v2, v2, v2 quad_perm:[1,0,3,2] row_mask:0xf bank_mask:0xf
	s_nop 1
	v_add_f32_dpp v2, v2, v2 quad_perm:[2,3,0,1] row_mask:0xf bank_mask:0xf
	s_nop 1
	v_add_f32_dpp v2, v2, v2 row_half_mirror row_mask:0xf bank_mask:0xf
	s_nop 1
	v_add_f32_dpp v2, v2, v2 row_mirror row_mask:0xf bank_mask:0xf
	v_fmamk_f32 v2, v2, 0x3c800000, v234
	v_mul_f32_e32 v5, 0x4f800000, v2
	v_cmp_gt_f32_e32 vcc, s3, v2
	s_nop 1
	v_cndmask_b32_e32 v2, v2, v5, vcc
	v_sqrt_f32_e32 v5, v2
	s_nop 0
	v_add_u32_e32 v20, -1, v5
	v_add_u32_e32 v22, 1, v5
	v_fma_f32 v57, -v20, v5, v2
	v_fma_f32 v59, -v22, v5, v2
	v_cmp_ge_f32_e64 s[62:63], 0, v57
	s_nop 1
	v_cndmask_b32_e64 v5, v5, v20, s[62:63]
	v_cmp_lt_f32_e64 s[62:63], 0, v59
	s_nop 1
	v_cndmask_b32_e64 v5, v5, v22, s[62:63]
	v_mul_f32_e32 v20, 0x37800000, v5
	v_cndmask_b32_e32 v5, v5, v20, vcc
	v_cmp_class_f32_e32 vcc, v2, v235
	v_mov_b32_e32 v20, v23
	s_nop 0
	v_cndmask_b32_e32 v2, v5, v2, vcc
	v_div_scale_f32 v5, s[12:13], v2, v2, 1.0
	v_rcp_f32_e32 v22, v5
	v_div_scale_f32 v23, vcc, 1.0, v2, 1.0
	v_fma_f32 v57, -v5, v22, 1.0
	v_fmac_f32_e32 v22, v57, v22
	v_mul_f32_e32 v57, v23, v22
	v_fma_f32 v59, -v5, v57, v23
	v_fmac_f32_e32 v57, v59, v22
	v_fma_f32 v5, -v5, v57, v23
	v_div_fmas_f32 v5, v5, v22, v57
	v_div_fixup_f32 v2, v5, v2, 1.0
	v_pk_mul_f32 v[22:23], v[2:3], v[76:77] op_sel_hi:[0,1]
	v_pk_mul_f32 v[20:21], v[2:3], v[20:21] op_sel_hi:[0,1]
	v_pk_mul_f32 v[18:19], v[114:115], v[20:21]
	v_pk_mul_f32 v[16:17], v[112:113], v[22:23]
	s_mov_b64 vcc, s[60:61]
	s_cbranch_vccnz .LBB0_460
	s_lshl_b32 s90, s20, 2
	v_lshl_add_u64 v[20:21], v[62:63], 0, s[90:91]
	global_store_dwordx4 v[20:21], v[16:19], off
.LBB0_460:
	ds_bpermute_b32 v20, v70, v16
	ds_bpermute_b32 v22, v70, v18
	ds_bpermute_b32 v23, v70, v19
	ds_bpermute_b32 v21, v70, v17
	v_mov_b32_e32 v57, v3
	v_lshl_add_u64 v[76:77], s[10:11], 0, v[56:57]
	s_lshl_b64 s[12:13], s[8:9], 9
	s_waitcnt lgkmcnt(1)
	v_pk_mul_f32 v[22:23], v[14:15], v[22:23]
	s_waitcnt lgkmcnt(0)
	v_pk_mul_f32 v[20:21], v[12:13], v[20:21]
	v_xor_b32_e32 v57, 0x80000000, v22
	v_xor_b32_e32 v2, 0x80000000, v20
	v_xor_b32_e32 v5, 0x80000000, v21
	v_xor_b32_e32 v59, 0x80000000, v23
	v_cndmask_b32_e64 v23, v23, v59, s[52:53]
	v_cndmask_b32_e64 v22, v22, v57, s[52:53]
	v_cndmask_b32_e64 v21, v21, v5, s[52:53]
	v_cndmask_b32_e64 v20, v20, v2, s[52:53]
	v_pk_fma_f32 v[20:21], v[8:9], v[16:17], v[20:21]
	v_pk_fma_f32 v[22:23], v[10:11], v[18:19], v[22:23]
	v_cndmask_b32_e64 v17, v17, v21, s[58:59]
	v_cndmask_b32_e64 v2, v19, v23, s[58:59]
	v_cndmask_b32_e64 v5, v18, v22, s[58:59]
	v_cndmask_b32_e64 v16, v16, v20, s[58:59]
	v_cvt_pk_bf16_f32 v16, v16, v17
	v_cvt_pk_bf16_f32 v17, v5, v2
	v_lshl_add_u64 v[18:19], v[32:33], 0, s[12:13]
	global_store_dwordx2 v[18:19], v[16:17], off
	v_cndmask_b32_e64 v2, 0, 1, s[16:17]
	v_cmp_ne_u32_e64 s[60:61], 1, v2
	s_andn2_b64 vcc, exec, s[16:17]
	s_cbranch_vccnz .LBB0_462
	s_lshl_b32 s90, s20, 2
	v_and_b32_e32 v21, 0xffff0000, v117
	v_lshlrev_b32_e32 v20, 16, v117
	v_and_b32_e32 v19, 0xffff0000, v116
	v_lshlrev_b32_e32 v18, 16, v116
	v_lshl_add_u64 v[22:23], v[64:65], 0, s[90:91]
	global_store_dwordx4 v[22:23], v[18:21], off
.LBB0_462:
	s_lshl_b32 s90, s21, 1
	s_nop 0
	v_lshl_add_u64 v[18:19], v[60:61], 0, s[90:91]
	global_store_short v[18:19], v116, off
	global_store_short_d16_hi v[18:19], v116, off offset:512
	global_store_short v[18:19], v117, off offset:1024
	global_store_short_d16_hi v[18:19], v117, off offset:1536
	s_nop 0
	s_lshl_b64 s[12:13], s[8:9], 10
	v_lshlrev_b32_e32 v84, 16, v120
	v_and_b32_e32 v85, 0xffff0000, v120
	v_lshlrev_b32_e32 v80, 16, v123
	v_and_b32_e32 v81, 0xffff0000, v123
	v_lshlrev_b32_e32 v82, 16, v122
	v_and_b32_e32 v83, 0xffff0000, v122
	v_lshlrev_b32_e32 v18, 16, v121
	v_and_b32_e32 v19, 0xffff0000, v121
	v_pk_mul_f32 v[90:91], v[84:85], v[84:85]
	v_pk_mul_f32 v[88:89], v[18:19], v[18:19]
	v_add_f32_e32 v2, v90, v91
	v_add_f32_e32 v2, v88, v2
	v_pk_mul_f32 v[86:87], v[82:83], v[82:83]
	v_add_f32_e32 v2, v89, v2
	v_add_f32_e32 v2, v86, v2
	v_pk_mul_f32 v[16:17], v[80:81], v[80:81]
	v_add_f32_e32 v2, v87, v2
	v_add_f32_e32 v2, v16, v2
	v_add_f32_e32 v2, v17, v2
	v_lshl_add_u64 v[86:87], v[38:39], 0, s[12:13]
	s_nop 1
	v_add_f32_dpp v2, v2, v2 quad_perm:[1,0,3,2] row_mask:0xf bank_mask:0xf
	s_nop 1
	v_add_f32_dpp v2, v2, v2 quad_perm:[2,3,0,1] row_mask:0xf bank_mask:0xf
	s_nop 1
	v_add_f32_dpp v2, v2, v2 row_half_mirror row_mask:0xf bank_mask:0xf
	s_nop 1
	v_add_f32_dpp v2, v2, v2 row_mirror row_mask:0xf bank_mask:0xf
	ds_bpermute_b32 v5, v72, v2
	s_waitcnt lgkmcnt(0)
	v_add_f32_e32 v2, v2, v5
	ds_bpermute_b32 v16, v73, v2
	v_mov_b32_e32 v5, v3
	s_waitcnt lgkmcnt(0)
	v_add_f32_e32 v2, v2, v16
	v_fmamk_f32 v2, v2, 0x3b000000, v234
	v_mul_f32_e32 v16, 0x4f800000, v2
	v_cmp_gt_f32_e32 vcc, s3, v2
	s_nop 1
	v_cndmask_b32_e32 v2, v2, v16, vcc
	v_sqrt_f32_e32 v57, v2
	v_lshl_add_u64 v[16:17], s[10:11], 0, v[4:5]
	v_add_u32_e32 v5, -1, v57
	v_add_u32_e32 v59, 1, v57
	v_fma_f32 v75, -v5, v57, v2
	v_fma_f32 v88, -v59, v57, v2
	v_cmp_ge_f32_e64 s[62:63], 0, v75
	s_nop 1
	v_cndmask_b32_e64 v5, v57, v5, s[62:63]
	v_cmp_lt_f32_e64 s[62:63], 0, v88
	s_nop 1
	v_cndmask_b32_e64 v5, v5, v59, s[62:63]
	v_mul_f32_e32 v57, 0x37800000, v5
	v_cndmask_b32_e32 v5, v5, v57, vcc
	v_cmp_class_f32_e32 vcc, v2, v235
	s_nop 1
	v_cndmask_b32_e32 v2, v5, v2, vcc
	v_div_scale_f32 v5, s[16:17], v2, v2, 1.0
	v_rcp_f32_e32 v57, v5
	v_add_co_u32_e32 v88, vcc, s28, v16
	s_nop 1
	v_addc_co_u32_e32 v89, vcc, 0, v17, vcc
	v_fma_f32 v17, -v5, v57, 1.0
	v_div_scale_f32 v16, vcc, 1.0, v2, 1.0
	v_fmac_f32_e32 v57, v17, v57
	v_mul_f32_e32 v17, v16, v57
	v_fma_f32 v59, -v5, v17, v16
	v_fmac_f32_e32 v17, v59, v57
	v_fma_f32 v5, -v5, v17, v16
	v_div_fmas_f32 v5, v5, v57, v17
	v_div_fixup_f32 v2, v5, v2, 1.0
	v_pk_mul_f32 v[16:17], v[128:129], v[2:3] op_sel_hi:[1,0]
	v_pk_mul_f32 v[76:77], v[130:131], v[2:3] op_sel_hi:[1,0]
	v_pk_mul_f32 v[20:21], v[124:125], v[2:3] op_sel_hi:[1,0]
	v_pk_mul_f32 v[22:23], v[126:127], v[2:3] op_sel_hi:[1,0]
	v_pk_mul_f32 v[16:17], v[16:17], v[84:85]
	v_pk_mul_f32 v[18:19], v[76:77], v[18:19]
	v_pk_mul_f32 v[20:21], v[20:21], v[82:83]
	v_pk_mul_f32 v[22:23], v[22:23], v[80:81]
	v_cvt_pk_bf16_f32 v16, v16, v17
	v_cvt_pk_bf16_f32 v17, v18, v19
	v_cvt_pk_bf16_f32 v18, v20, v21
	v_cvt_pk_bf16_f32 v19, v22, v23
	global_store_dwordx4 v[86:87], v[16:19], off
	s_nop 0
	v_lshlrev_b32_e32 v80, 16, v132
	v_and_b32_e32 v81, 0xffff0000, v132
	v_lshlrev_b32_e32 v16, 16, v133
	v_and_b32_e32 v17, 0xffff0000, v133
	v_pk_mul_f32 v[84:85], v[80:81], v[80:81]
	v_pk_mul_f32 v[86:87], v[16:17], v[16:17]
	v_add_f32_e32 v2, v84, v85
	v_lshlrev_b32_e32 v82, 16, v134
	v_and_b32_e32 v83, 0xffff0000, v134
	v_add_f32_e32 v2, v86, v2
	v_pk_mul_f32 v[88:89], v[82:83], v[82:83]
	v_add_f32_e32 v2, v87, v2
	v_lshlrev_b32_e32 v18, 16, v135
	v_and_b32_e32 v19, 0xffff0000, v135
	v_add_f32_e32 v2, v88, v2
	v_pk_mul_f32 v[90:91], v[18:19], v[18:19]
	v_add_f32_e32 v2, v89, v2
	v_add_f32_e32 v2, v90, v2
	v_add_f32_e32 v2, v91, v2
	s_nop 1
	v_add_f32_dpp v2, v2, v2 quad_perm:[1,0,3,2] row_mask:0xf bank_mask:0xf
	s_nop 1
	v_add_f32_dpp v2, v2, v2 quad_perm:[2,3,0,1] row_mask:0xf bank_mask:0xf
	s_nop 1
	v_add_f32_dpp v2, v2, v2 row_half_mirror row_mask:0xf bank_mask:0xf
	s_nop 1
	v_add_f32_dpp v2, v2, v2 row_mirror row_mask:0xf bank_mask:0xf
	ds_bpermute_b32 v5, v72, v2
	s_waitcnt lgkmcnt(0)
	v_add_f32_e32 v2, v2, v5
	ds_bpermute_b32 v5, v73, v2
	s_waitcnt lgkmcnt(0)
	v_add_f32_e32 v2, v2, v5
	v_fmamk_f32 v2, v2, 0x3b000000, v234
	v_mul_f32_e32 v5, 0x4f800000, v2
	v_cmp_gt_f32_e32 vcc, s3, v2
	s_nop 1
	v_cndmask_b32_e32 v2, v2, v5, vcc
	v_sqrt_f32_e32 v5, v2
	s_nop 0
	v_add_u32_e32 v57, -1, v5
	v_add_u32_e32 v59, 1, v5
	v_fma_f32 v75, -v57, v5, v2
	v_fma_f32 v84, -v59, v5, v2
	v_cmp_ge_f32_e64 s[62:63], 0, v75
	s_nop 1
	v_cndmask_b32_e64 v5, v5, v57, s[62:63]
	v_cmp_lt_f32_e64 s[62:63], 0, v84
	v_lshl_add_u64 v[84:85], v[42:43], 0, s[12:13]
	s_nop 0
	v_cndmask_b32_e64 v5, v5, v59, s[62:63]
	v_mul_f32_e32 v57, 0x37800000, v5
	v_cndmask_b32_e32 v5, v5, v57, vcc
	v_cmp_class_f32_e32 vcc, v2, v235
	s_nop 1
	v_cndmask_b32_e32 v2, v5, v2, vcc
	v_div_scale_f32 v5, s[16:17], v2, v2, 1.0
	v_rcp_f32_e32 v57, v5
	v_div_scale_f32 v59, vcc, 1.0, v2, 1.0
	v_fma_f32 v75, -v5, v57, 1.0
	v_fmac_f32_e32 v57, v75, v57
	v_mul_f32_e32 v75, v59, v57
	v_fma_f32 v86, -v5, v75, v59
	v_fmac_f32_e32 v75, v86, v57
	v_fma_f32 v5, -v5, v75, v59
	v_div_fmas_f32 v5, v5, v57, v75
	v_div_fixup_f32 v2, v5, v2, 1.0
	v_pk_mul_f32 v[76:77], v[140:141], v[2:3] op_sel_hi:[1,0]
	v_pk_mul_f32 v[78:79], v[142:143], v[2:3] op_sel_hi:[1,0]
	v_pk_mul_f32 v[86:87], v[136:137], v[2:3] op_sel_hi:[1,0]
	v_pk_mul_f32 v[88:89], v[138:139], v[2:3] op_sel_hi:[1,0]
	v_pk_mul_f32 v[20:21], v[76:77], v[80:81]
	v_pk_mul_f32 v[22:23], v[78:79], v[16:17]
	v_pk_mul_f32 v[16:17], v[86:87], v[82:83]
	v_pk_mul_f32 v[18:19], v[88:89], v[18:19]
	v_cvt_pk_bf16_f32 v76, v20, v21
	v_cvt_pk_bf16_f32 v77, v22, v23
	v_cvt_pk_bf16_f32 v78, v16, v17
	v_cvt_pk_bf16_f32 v79, v18, v19
	s_and_b64 vcc, exec, s[60:61]
	global_store_dwordx4 v[84:85], v[76:79], off
	s_cbranch_vccnz .LBB0_464
	s_lshl_b32 s90, s21, 11
	v_lshl_add_u64 v[76:77], v[66:67], 0, s[90:91]
	global_store_dwordx4 v[76:77], v[20:23], off
	global_store_dwordx4 v[76:77], v[16:19], off offset:16
.LBB0_464:
	v_mov_b32_e32 v59, v3
	s_nop 0
	v_lshl_add_u64 v[16:17], s[10:11], 0, v[58:59]
	v_add_co_u32_e32 v16, vcc, 0x1000, v16
	s_nor_b64 s[12:13], s[54:55], s[58:59]
	s_nop 0
	v_addc_co_u32_e32 v17, vcc, 0, v17, vcc
	v_lshlrev_b32_e32 v16, 16, v144
	v_and_b32_e32 v17, 0xffff0000, v144
	v_lshlrev_b32_e32 v18, 16, v145
	v_and_b32_e32 v19, 0xffff0000, v145
	s_and_saveexec_b64 s[10:11], s[12:13]
	s_cbranch_execz .LBB0_466
	s_mov_b32 s21, s91
	v_lshl_add_u64 v[20:21], v[68:69], 0, s[20:21]
	global_store_dwordx4 v[20:21], v[16:19], off
